# pool_stage WPOOL loads hoisted to start of pooling stage (overlap with pooling/POOLEDS round trips)
# baseline (speedup 1.0000x reference)
.LBB0_380:
	v_add_u32_e32 v133, s97, v170
	v_add_u32_e32 v134, s59, v133
	s_add_u32 s6, s92, 0xca00000
	s_mov_b32 s0, 0x20000
	s_addc_u32 s7, s93, 0
	v_cmp_gt_i32_e32 vcc, s0, v134
	s_barrier
	s_and_b64 s[34:35], exec, s[4:5]
	s_cbranch_scc0 .Lps_hoist_skip
	s_ashr_i32 s10, s33, 6
	s_ashr_i32 s11, s10, 31
	s_lshl_b64 s[10:11], s[10:11], 17
	s_add_u32 s10, s68, s10
	s_addc_u32 s11, s69, s11
	v_lshlrev_b32_e32 v244, 3, v133
	v_lshlrev_b32_e32 v240, 4, v133
	v_and_b32_e32 v240, 0x1f0, v240
	v_mov_b32_e32 v241, 0
	v_and_b32_e32 v244, 0xffffff00, v244
	v_lshl_add_u64 v[240:241], s[10:11], 0, v[240:241]
	v_mov_b32_e32 v242, v244
	v_ashrrev_i32_e32 v243, 31, v242
	v_lshl_add_u64 v[242:243], v[242:243], 1, v[240:241]
	global_load_dwordx4 v[172:175], v[242:243], off
	v_add_u32_e32 v246, 0x1000, v244
	v_ashrrev_i32_e32 v247, 31, v246
	v_lshl_add_u64 v[246:247], v[246:247], 1, v[240:241]
	global_load_dwordx4 v[176:179], v[246:247], off
	v_add_u32_e32 v242, 0x2000, v244
	v_ashrrev_i32_e32 v243, 31, v242
	v_lshl_add_u64 v[242:243], v[242:243], 1, v[240:241]
	global_load_dwordx4 v[180:183], v[242:243], off
	v_add_u32_e32 v246, 0x3000, v244
	v_ashrrev_i32_e32 v247, 31, v246
	v_lshl_add_u64 v[246:247], v[246:247], 1, v[240:241]
	global_load_dwordx4 v[184:187], v[246:247], off
	v_add_u32_e32 v242, 0x4000, v244
	v_ashrrev_i32_e32 v243, 31, v242
	v_lshl_add_u64 v[242:243], v[242:243], 1, v[240:241]
	global_load_dwordx4 v[188:191], v[242:243], off
	v_add_u32_e32 v246, 0x5000, v244
	v_ashrrev_i32_e32 v247, 31, v246
	v_lshl_add_u64 v[246:247], v[246:247], 1, v[240:241]
	global_load_dwordx4 v[192:195], v[246:247], off
	v_add_u32_e32 v242, 0x6000, v244
	v_ashrrev_i32_e32 v243, 31, v242
	v_lshl_add_u64 v[242:243], v[242:243], 1, v[240:241]
	global_load_dwordx4 v[196:199], v[242:243], off
	v_add_u32_e32 v246, 0x7000, v244
	v_ashrrev_i32_e32 v247, 31, v246
	v_lshl_add_u64 v[246:247], v[246:247], 1, v[240:241]
	global_load_dwordx4 v[200:203], v[246:247], off
	v_add_u32_e32 v242, 0x8000, v244
	v_ashrrev_i32_e32 v243, 31, v242
	v_lshl_add_u64 v[242:243], v[242:243], 1, v[240:241]
	global_load_dwordx4 v[204:207], v[242:243], off
	v_add_u32_e32 v246, 0x9000, v244
	v_ashrrev_i32_e32 v247, 31, v246
	v_lshl_add_u64 v[246:247], v[246:247], 1, v[240:241]
	global_load_dwordx4 v[208:211], v[246:247], off
	v_add_u32_e32 v242, 0xa000, v244
	v_ashrrev_i32_e32 v243, 31, v242
	v_lshl_add_u64 v[242:243], v[242:243], 1, v[240:241]
	global_load_dwordx4 v[212:215], v[242:243], off
	v_add_u32_e32 v246, 0xb000, v244
	v_ashrrev_i32_e32 v247, 31, v246
	v_lshl_add_u64 v[246:247], v[246:247], 1, v[240:241]
	global_load_dwordx4 v[216:219], v[246:247], off
	v_add_u32_e32 v242, 0xc000, v244
	v_ashrrev_i32_e32 v243, 31, v242
	v_lshl_add_u64 v[242:243], v[242:243], 1, v[240:241]
	global_load_dwordx4 v[220:223], v[242:243], off
	v_add_u32_e32 v246, 0xd000, v244
	v_ashrrev_i32_e32 v247, 31, v246
	v_lshl_add_u64 v[246:247], v[246:247], 1, v[240:241]
	global_load_dwordx4 v[224:227], v[246:247], off
	v_add_u32_e32 v242, 0xe000, v244
	v_ashrrev_i32_e32 v243, 31, v242
	v_lshl_add_u64 v[242:243], v[242:243], 1, v[240:241]
	global_load_dwordx4 v[228:231], v[242:243], off
	v_add_u32_e32 v246, 0xf000, v244
	v_ashrrev_i32_e32 v247, 31, v246
	v_lshl_add_u64 v[246:247], v[246:247], 1, v[240:241]
	global_load_dwordx4 v[232:235], v[246:247], off
.Lps_hoist_skip:
	s_and_saveexec_b64 s[8:9], vcc
	v_readlane_b32 s86, v238, 13
	v_readlane_b32 s87, v238, 14
	s_cbranch_execz .LBB0_455
	s_add_u32 s10, s92, 0x4602000
	s_addc_u32 s11, s93, 0
	v_lshlrev_b32_e32 v135, 3, v134
	s_lshl_b32 s43, s94, 12
	s_mov_b64 s[40:41], 0
	v_mov_b32_e32 v93, 0
	s_mov_b32 s42, 0x3e000000
	s_mov_b32 s54, 0x3e800000
	v_mov_b32_e32 v136, v134
	s_branch .LBB0_384

.LBB0_498:
	s_or_b64 exec, exec, s[10:11]
	s_and_b64 vcc, exec, s[4:5]
	s_cbranch_vccz .LBB0_500
	s_waitcnt vmcnt(0)
	s_barrier
	s_cmp_lg_u32 s81, 0
	s_cbranch_scc1 .Lp2_noarrive
	s_mov_b64 s[10:11], exec
	s_mov_b64 exec, 1
	v_mov_b32_e32 v252, 0x3000
	v_mov_b32_e32 v253, 1
	global_atomic_add v252, v253, s[92:93]
	s_mov_b64 exec, s[10:11]
.Lp2_noarrive:
	v_and_b32_e32 v64, 0x1f0, v132
	v_add_u32_e32 v64, 0, v64
	v_ashrrev_i32_e32 v65, 5, v133
	s_movk_i32 s10, 0x210
	v_mad_u64_u32 v[66:67], s[0:1], v65, s10, v[64:65]
	ds_write_b128 v66, v[172:175]
	v_add_u32_e32 v0, 0x200, v133
	v_ashrrev_i32_e32 v0, 5, v0
	v_mad_u64_u32 v[0:1], s[0:1], v0, s10, v[64:65]
	ds_write_b128 v0, v[176:179]
	v_add_u32_e32 v0, 0x400, v133
	v_ashrrev_i32_e32 v0, 5, v0
	v_mad_u64_u32 v[0:1], s[0:1], v0, s10, v[64:65]
	ds_write_b128 v0, v[180:183]
	v_add_u32_e32 v0, 0x600, v133
	v_ashrrev_i32_e32 v0, 5, v0
	v_mad_u64_u32 v[0:1], s[0:1], v0, s10, v[64:65]
	ds_write_b128 v0, v[184:187]
	v_add_u32_e32 v0, 0x800, v133
	v_ashrrev_i32_e32 v0, 5, v0
	v_mad_u64_u32 v[0:1], s[0:1], v0, s10, v[64:65]
	ds_write_b128 v0, v[188:191]
	v_add_u32_e32 v0, 0xa00, v133
	v_ashrrev_i32_e32 v0, 5, v0
	v_mad_u64_u32 v[0:1], s[0:1], v0, s10, v[64:65]
	ds_write_b128 v0, v[192:195]
	v_add_u32_e32 v0, 0xc00, v133
	v_ashrrev_i32_e32 v0, 5, v0
	v_mad_u64_u32 v[0:1], s[0:1], v0, s10, v[64:65]
	ds_write_b128 v0, v[196:199]
	v_add_u32_e32 v0, 0xe00, v133
	v_ashrrev_i32_e32 v0, 5, v0
	v_mad_u64_u32 v[0:1], s[0:1], v0, s10, v[64:65]
	ds_write_b128 v0, v[200:203]
	v_add_u32_e32 v0, 0x1000, v133
	v_ashrrev_i32_e32 v0, 5, v0
	v_mad_u64_u32 v[0:1], s[0:1], v0, s10, v[64:65]
	ds_write_b128 v0, v[204:207]
	v_add_u32_e32 v0, 0x1200, v133
	v_ashrrev_i32_e32 v0, 5, v0
	v_mad_u64_u32 v[0:1], s[0:1], v0, s10, v[64:65]
	ds_write_b128 v0, v[208:211]
	v_add_u32_e32 v0, 0x1400, v133
	v_ashrrev_i32_e32 v0, 5, v0
	v_mad_u64_u32 v[0:1], s[0:1], v0, s10, v[64:65]
	ds_write_b128 v0, v[212:215]
	v_add_u32_e32 v0, 0x1600, v133
	v_ashrrev_i32_e32 v0, 5, v0
	v_mad_u64_u32 v[0:1], s[0:1], v0, s10, v[64:65]
	ds_write_b128 v0, v[216:219]
	v_add_u32_e32 v0, 0x1800, v133
	v_ashrrev_i32_e32 v0, 5, v0
	v_mad_u64_u32 v[0:1], s[0:1], v0, s10, v[64:65]
	ds_write_b128 v0, v[220:223]
	v_add_u32_e32 v0, 0x1a00, v133
	v_ashrrev_i32_e32 v0, 5, v0
	v_mad_u64_u32 v[0:1], s[0:1], v0, s10, v[64:65]
	ds_write_b128 v0, v[224:227]
	v_add_u32_e32 v0, 0x1c00, v133
	v_ashrrev_i32_e32 v0, 5, v0
	v_mad_u64_u32 v[0:1], s[0:1], v0, s10, v[64:65]
	ds_write_b128 v0, v[228:231]
	v_add_u32_e32 v0, 0x1e00, v133
	v_ashrrev_i32_e32 v0, 5, v0
	v_mad_u64_u32 v[0:1], s[0:1], v0, s10, v[64:65]
	ds_write_b128 v0, v[232:235]
.LBB0_500:
	s_waitcnt lgkmcnt(0)
	s_barrier
	s_mov_b64 s[10:11], exec
	v_readlane_b32 s0, v239, 0
	v_readlane_b32 s1, v239, 1
	s_and_b64 s[0:1], s[10:11], s[0:1]
	s_mov_b64 exec, s[0:1]
	s_branch .LBB0_552
